# flag-based group seams with the L1 invalidate issued right after the flag store (overlaps the poll)
# speedup vs baseline: 1.0081x; 1.0033x over previous
.Llb_have:
	global_atomic_add v2, v1, s[10:11]
	v_readlane_b32 s17, v252, 0
	s_nop 0
	s_lshr_b32 s16, s17, 3
	s_lshl_b32 s16, s16, 2
	s_lshl_b32 s17, s8, 7
	s_add_i32 s17, s17, 0x500
	s_add_i32 s16, s16, s17
	v_mov_b32_e32 v2, s16
	s_add_i32 s15, s6, 1
	v_mov_b32_e32 v3, s15
	s_nop 0
	global_store_dword v2, v3, s[10:11]
	buffer_inv sc1
	s_mov_b64 exec, 0xffffffff
	v_mbcnt_lo_u32_b32 v2, -1, 0
	v_lshl_add_u32 v2, v2, 2, s17
	s_mov_b32 s12, 0
